# in-proj unit order: pn slots permuted so V,V,F,F share round 2 and conv units fill round 3
# baseline (speedup 1.0000x reference)
.LBB0_137:
	s_andn2_b64 vcc, exec, s[2:3]
	s_cbranch_vccnz .LBB0_1033
	v_bfe_i32 v1, v5, 27, 1
	v_lshlrev_b32_e32 v3, 4, v5
	v_lshrrev_b32_e32 v1, 22, v1
	v_add_u32_e32 v1, v3, v1
	v_and_b32_e32 v1, 0xfffffc00, v1
	v_sub_u32_e32 v1, v3, v1
	v_lshrrev_b32_e32 v2, 4, v1
	v_bitop3_b32 v2, v2, v1, 32 bitop3:0x6c
	v_ashrrev_i32_e32 v1, 31, v1
	v_lshrrev_b32_e32 v1, 26, v1
	v_ashrrev_i32_e32 v0, 31, v5
	v_add_u32_e32 v1, v2, v1
	v_lshrrev_b32_e32 v0, 26, v0
	v_ashrrev_i32_e32 v1, 6, v1
	v_add_u32_e32 v0, v5, v0
	v_mul_i32_i24_e32 v7, 64, v1
	v_ashrrev_i32_e32 v0, 6, v0
	v_sub_u32_e32 v2, v2, v7
	v_lshlrev_b32_e32 v4, 3, v0
	v_lshlrev_b32_e32 v6, 5, v0
	v_ashrrev_i16_sdwa v2, v205, sext(v2) dst_sel:DWORD dst_unused:UNUSED_PAD src0_sel:DWORD src1_sel:BYTE_0
	v_and_b32_e32 v4, 0x1ffff0, v4
	v_and_b32_e32 v6, 32, v6
	v_bfe_i32 v2, v2, 0, 16
	v_add_u32_e32 v6, v6, v2
	v_add_lshl_u32 v4, v1, v4, 11
	v_lshl_add_u32 v150, v6, 1, v4
	v_add_u32_e32 v4, 0x2000, v3
	v_ashrrev_i32_e32 v3, 31, v4
	v_lshrrev_b32_e32 v3, 22, v3
	v_add_u32_e32 v3, v4, v3
	v_ashrrev_i32_e32 v3, 10, v3
	v_mul_i32_i24_e32 v6, 0x400, v3
	s_add_u32 s86, s80, 0x62a4400
	v_sub_u32_e32 v4, v4, v6
	v_writelane_b32 v254, s82, 51
	s_addc_u32 s87, s81, 0
	s_mul_i32 s3, s40, 0x580000
	v_lshrrev_b32_e32 v6, 4, v4
	v_writelane_b32 v254, s83, 52
	s_mul_hi_u32 s2, s40, 0x580000
	s_add_u32 s3, s80, s3
	v_bitop3_b32 v6, v6, v4, 32 bitop3:0x6c
	v_lshlrev_b32_e32 v4, 3, v3
	v_writelane_b32 v254, s80, 61
	s_addc_u32 s2, s81, s2
	v_and_b32_e32 v7, 0x1ffff0, v4
	v_ashrrev_i32_e32 v4, 31, v6
	v_writelane_b32 v254, s81, 62
	s_add_u32 s41, s3, 0x4200000
	v_lshrrev_b32_e32 v4, 26, v4
	s_addc_u32 s14, s2, 0
	s_ashr_i32 s4, s9, 8
	s_waitcnt vmcnt(1)
	v_add_u32_e32 v8, v6, v4
	v_writelane_b32 v254, s9, 53
	s_ashr_i32 s5, s9, 6
	s_ashr_i32 s9, s8, 31
	s_cmp_gt_u32 s26, 7
	s_cselect_b32 s27, -5, 0
	s_add_i32 s27, s27, 3
	s_cmp_gt_u32 s26, 5
	s_cselect_b32 s27, s27, 0
	s_add_i32 s26, s26, s27
	s_ashr_i32 s27, s26, 31
	v_ashrrev_i32_e32 v4, 6, v8
	v_and_b32_e32 v8, 0xc0, v8
	s_lshl_b32 s15, s5, 10
	s_lshl_b64 s[2:3], s[8:9], 19
	s_lshl_b64 s[6:7], s[26:27], 19
	v_sub_u32_e32 v6, v6, v8
	s_add_u32 s6, s41, s6
	v_lshlrev_b32_e32 v9, 5, v3
	v_ashrrev_i16_sdwa v6, v205, sext(v6) dst_sel:DWORD dst_unused:UNUSED_PAD src0_sel:DWORD src1_sel:BYTE_0
	s_addc_u32 s7, s14, s7
	s_add_i32 s50, s15, 0
	v_and_b32_e32 v9, 32, v9
	v_bfe_i32 v6, v6, 0, 16
	s_add_i32 m0, s50, 0x10000
	v_add_u32_e32 v8, v9, v6
	v_add_lshl_u32 v7, v4, v7, 11
	global_load_lds_dwordx4 v150, s[6:7]
	s_add_i32 m0, s50, 0x12000
	v_lshl_add_u32 v152, v8, 1, v7
	s_add_u32 s2, s86, s2
	global_load_lds_dwordx4 v152, s[6:7]
	s_addc_u32 s3, s87, s3
	s_mov_b32 m0, s50
	s_add_i32 s51, s50, 0x2000
	global_load_lds_dwordx4 v150, s[2:3]
	s_mov_b32 m0, s51
	s_add_u32 s10, s6, 0x40000
	global_load_lds_dwordx4 v152, s[2:3]
	s_addc_u32 s11, s7, 0
	s_add_i32 m0, s50, 0x14000
	v_mov_b32_e32 v203, 0x1000
	global_load_lds_dwordx4 v150, s[10:11]
	s_add_i32 m0, s50, 0x16000
	s_nop 0
	global_load_lds_dwordx4 v152, s[10:11]
	s_add_u32 s10, s2, 0x40000
	s_addc_u32 s11, s3, 0
	s_add_i32 s36, s50, 0x4000
	s_mov_b32 m0, s36
	s_add_i32 s37, s50, 0x6000
	global_load_lds_dwordx4 v150, s[10:11]
	s_mov_b32 m0, s37
	s_cmp_lg_u32 s4, 1
	global_load_lds_dwordx4 v152, s[10:11]
	s_cbranch_scc1 .LBB0_140
	s_barrier

.LBB0_144:
	s_ashr_i32 s19, s18, 31
	v_cmp_lt_i64_e32 vcc, s[10:11], v[140:141]
	s_lshl_b64 s[10:11], s[18:19], 19
	s_add_u32 s22, s86, s10
	s_addc_u32 s23, s87, s11
	s_and_b64 s[10:11], vcc, exec
	s_cselect_b32 s9, s23, s3
	s_cselect_b32 s12, s22, s2
	s_cmp_gt_u32 s16, 7
	s_cselect_b32 s17, -5, 0
	s_add_i32 s17, s17, 3
	s_cmp_gt_u32 s16, 5
	s_cselect_b32 s17, s17, 0
	s_add_i32 s16, s16, s17
	s_ashr_i32 s17, s16, 31
	s_lshl_b64 s[10:11], s[16:17], 19
	s_add_u32 s24, s41, s10
	s_addc_u32 s25, s14, s11
	s_and_b64 s[10:11], vcc, exec
	s_cselect_b32 s13, s25, s7
	s_cselect_b32 s17, s24, s6
	s_add_u32 s2, s2, 0x40080
	s_addc_u32 s3, s3, 0
	s_add_u32 s19, s6, 0x100
	v_mov_b32_e32 v0, 0
	s_addc_u32 s27, s7, 0
	s_waitcnt lgkmcnt(0)
	s_mov_b32 s28, -2
	v_mov_b32_e32 v1, v0
	v_mov_b64_e32 v[2:3], 0
	v_mov_b64_e32 v[4:5], 0
	v_mov_b64_e32 v[6:7], 0
	v_mov_b64_e32 v[8:9], 0
	v_mov_b64_e32 v[10:11], 0
	v_mov_b64_e32 v[12:13], 0
	v_mov_b64_e32 v[14:15], 0
	v_mov_b64_e32 v[16:17], 0
	v_mov_b64_e32 v[18:19], 0
	v_mov_b64_e32 v[20:21], 0
	v_mov_b64_e32 v[22:23], 0
	v_mov_b64_e32 v[24:25], 0
	v_mov_b64_e32 v[26:27], 0
	v_mov_b64_e32 v[28:29], 0
	v_mov_b64_e32 v[30:31], 0
	v_mov_b64_e32 v[32:33], 0
	v_mov_b64_e32 v[34:35], 0
	v_mov_b64_e32 v[36:37], 0
	v_mov_b64_e32 v[38:39], 0
	v_mov_b64_e32 v[40:41], 0
	v_mov_b64_e32 v[42:43], 0
	v_mov_b64_e32 v[44:45], 0
	v_mov_b64_e32 v[46:47], 0
	v_mov_b64_e32 v[48:49], 0
	v_mov_b64_e32 v[50:51], 0
	v_mov_b64_e32 v[52:53], 0
	v_mov_b64_e32 v[54:55], 0
	v_mov_b64_e32 v[56:57], 0
	v_mov_b64_e32 v[58:59], 0
	v_mov_b64_e32 v[60:61], 0
	v_mov_b64_e32 v[62:63], 0
	v_mov_b64_e32 v[64:65], 0
	v_mov_b64_e32 v[66:67], 0
	v_mov_b64_e32 v[68:69], 0
	v_mov_b64_e32 v[70:71], 0
	v_mov_b64_e32 v[72:73], 0
	v_mov_b64_e32 v[74:75], 0
	v_mov_b64_e32 v[76:77], 0
	v_mov_b64_e32 v[78:79], 0
	v_mov_b64_e32 v[80:81], 0
	v_mov_b64_e32 v[82:83], 0
	v_mov_b64_e32 v[84:85], 0
	v_mov_b64_e32 v[86:87], 0
	v_mov_b64_e32 v[88:89], 0
	v_mov_b64_e32 v[90:91], 0
	v_mov_b64_e32 v[92:93], 0
	v_mov_b64_e32 v[94:95], 0
	v_mov_b64_e32 v[96:97], 0
	v_mov_b64_e32 v[98:99], 0
	v_mov_b64_e32 v[100:101], 0
	v_mov_b64_e32 v[102:103], 0
	v_mov_b64_e32 v[104:105], 0
	v_mov_b64_e32 v[106:107], 0
	v_mov_b64_e32 v[108:109], 0
	v_mov_b64_e32 v[110:111], 0
	v_mov_b64_e32 v[112:113], 0
	v_mov_b64_e32 v[114:115], 0
	v_mov_b64_e32 v[116:117], 0
	v_mov_b64_e32 v[118:119], 0
	v_mov_b64_e32 v[120:121], 0
	v_mov_b64_e32 v[122:123], 0
	v_mov_b64_e32 v[124:125], 0
	v_mov_b64_e32 v[126:127], 0
	v_add_u32_e32 v166, 0x10000, v215
	ds_read_b128 v[128:131], v166
	ds_read_b128 v[158:161], v166 offset:1024
	ds_read_b128 v[162:165], v166 offset:2048
	ds_read_b128 v[166:169], v166 offset:3072
